# GEMM phase prologues (kind 1 and 2): removed the compiler's blanket s_waitcnt vmcnt(0) after the second K-tile's loads; the counted vmcnt(6) already there is what the schedule needs
# baseline (speedup 1.0000x reference)
.LBB0_462:
	v_lshl_add_u64 v[8:9], s[20:21], 0, v[112:113]
	v_mov_b32_e32 v135, v113
	v_lshl_add_u64 v[10:11], s[20:21], 0, v[134:135]
	v_mov_b32_e32 v139, v113
	s_add_i32 m0, s27, 0x18000
	v_lshl_add_u64 v[8:9], v[8:9], 0, s[30:31]
	v_lshl_add_u64 v[16:17], s[18:19], 0, v[138:139]
	v_mov_b32_e32 v137, v113
	s_waitcnt vmcnt(2)
	s_barrier
	global_load_lds_dwordx4 v[8:9], off
	v_lshl_add_u64 v[8:9], v[10:11], 0, s[30:31]
	s_add_i32 m0, s27, 0x1a000
	s_add_i32 s45, s27, 0x8000
	v_lshl_add_u64 v[18:19], s[18:19], 0, v[136:137]
	global_load_lds_dwordx4 v[8:9], off
	v_lshl_add_u64 v[8:9], v[16:17], 0, s[30:31]
	s_mov_b32 m0, s45
	s_add_i32 s46, s27, 0xa000
	v_lshl_add_u64 v[12:13], s[0:1], 0, v[112:113]
	global_load_lds_dwordx4 v[8:9], off
	v_lshl_add_u64 v[8:9], v[18:19], 0, s[30:31]
	s_mov_b32 m0, s46
	v_lshl_add_u64 v[14:15], s[0:1], 0, v[134:135]
	global_load_lds_dwordx4 v[8:9], off
	s_add_i32 m0, s27, 0x1c000
	v_lshl_add_u64 v[8:9], v[12:13], 0, s[30:31]
	global_load_lds_dwordx4 v[8:9], off
	v_lshl_add_u64 v[8:9], v[14:15], 0, s[30:31]
	s_add_i32 m0, s27, 0x1e000
	v_readlane_b32 s0, v255, 0
	global_load_lds_dwordx4 v[8:9], off
	v_lshrrev_b32_e32 v8, 1, v0
	v_and_b32_e32 v8, 24, v8
	v_readlane_b32 s1, v255, 1
	v_and_b32_e32 v7, 15, v0
	v_lshlrev_b32_e32 v9, 1, v8
	v_lshlrev_b32_e32 v0, 2, v0
	s_xor_b64 s[12:13], s[0:1], -1
	v_lshl_or_b32 v154, s16, 6, v7
	v_lshl_or_b32 v7, v7, 6, v9
	s_lshl_b32 s0, s16, 13
	v_and_b32_e32 v0, 32, v0
	v_bitop3_b32 v9, v7, s0, v0 bitop3:0xde
	s_lshl_b32 s0, s15, 5
	s_and_b32 s0, s0, 0x60
	s_lshl_b32 s1, s0, 7
	v_bitop3_b32 v155, v7, s1, v0 bitop3:0xde
	v_add_u32_e32 v0, v6, v4
	s_waitcnt vmcnt(6)
	s_add_i32 s47, s34, -2
	v_add_lshl_u32 v4, v0, v5, 1
	v_add_u32_e32 v0, v3, v1
	s_cmpk_lt_u32 s14, 0x100
	v_mov_b32_e32 v5, v113
	v_add_lshl_u32 v0, v0, v2, 1
	v_mov_b32_e32 v1, v113
	s_cselect_b64 s[14:15], -1, 0
	v_or_b32_e32 v163, s0, v8
	v_lshl_add_u64 v[140:141], s[2:3], 0, v[4:5]
	v_lshl_add_u64 v[142:143], s[2:3], 0, v[0:1]
	s_mov_b32 s48, 0
	v_add_u32_e32 v165, 0x100, v9
	v_readlane_b32 s22, v253, 6
	v_readlane_b32 s23, v253, 11
	s_barrier
	s_branch .LBB0_465

.LBB0_660:
	s_add_i32 m0, s27, 0x18000
	v_lshl_add_u64 v[8:9], v[8:9], 0, s[30:31]
	s_waitcnt vmcnt(2)
	s_barrier
	global_load_lds_dwordx4 v[8:9], off
	v_lshl_add_u64 v[4:5], v[4:5], 0, s[30:31]
	s_add_i32 m0, s27, 0x1a000
	s_add_i32 s42, s27, 0x8000
	global_load_lds_dwordx4 v[4:5], off
	v_lshl_add_u64 v[4:5], v[6:7], 0, s[30:31]
	s_mov_b32 m0, s42
	s_add_i32 s43, s27, 0xa000
	global_load_lds_dwordx4 v[4:5], off
	v_lshl_add_u64 v[4:5], v[10:11], 0, s[30:31]
	s_mov_b32 m0, s43
	v_lshl_add_u64 v[2:3], v[2:3], 0, s[30:31]
	global_load_lds_dwordx4 v[4:5], off
	s_add_i32 m0, s27, 0x1c000
	v_lshl_add_u64 v[0:1], v[0:1], 0, s[30:31]
	global_load_lds_dwordx4 v[2:3], off
	s_add_i32 m0, s27, 0x1e000
	s_add_i32 s44, s34, -2
	global_load_lds_dwordx4 v[0:1], off
	v_lshrrev_b32_e32 v1, 1, v12
	v_and_b32_e32 v1, 24, v1
	v_and_b32_e32 v0, 15, v12
	v_lshlrev_b32_e32 v2, 1, v1
	v_lshl_or_b32 v146, s0, 6, v0
	v_lshl_or_b32 v0, v0, 6, v2
	v_lshlrev_b32_e32 v2, 2, v12
	s_lshl_b32 s0, s0, 13
	v_and_b32_e32 v2, 32, v2
	v_bitop3_b32 v3, v0, s0, v2 bitop3:0xde
	s_lshl_b32 s0, s1, 5
	s_and_b32 s0, s0, 0x60
	s_lshl_b32 s1, s0, 7
	v_bitop3_b32 v147, v0, s1, v2 bitop3:0xde
	s_cmpk_lt_u32 s3, 0x100
	v_readlane_b32 s1, v255, 9
	s_cselect_b64 s[16:17], -1, 0
	s_lshl_b32 s45, s1, 3
	v_cvt_f32_u32_e32 v0, s45
	v_or_b32_e32 v148, s0, v1
	s_sub_i32 s0, 0, s45
	s_waitcnt vmcnt(6)
	v_rcp_iflag_f32_e32 v0, v0
	s_lshr_b32 s46, s2, 3
	s_mov_b32 s3, s80
	s_and_b32 s47, s2, 6
	v_mul_f32_e32 v0, 0x4f7ffffe, v0
	v_cvt_u32_f32_e32 v0, v0
	s_add_i32 s48, s46, 1
	s_mov_b32 s49, 0
	v_add_u32_e32 v149, 0x100, v3
	v_readfirstlane_b32 s1, v0
	v_add_u32_e32 v0, v15, v13
	s_mul_i32 s0, s0, s1
	v_add_lshl_u32 v112, v0, v14, 1
	v_add_u32_e32 v0, v18, v16
	s_mul_hi_u32 s0, s1, s0
	v_lshl_add_u64 v[140:141], s[10:11], 0, v[112:113]
	v_add_lshl_u32 v112, v0, v17, 1
	s_add_i32 s50, s1, s0
	v_lshl_add_u64 v[142:143], s[10:11], 0, v[112:113]
	s_barrier
	s_branch .LBB0_663
